# attention tile loop: waves 4-7 run half an iteration behind waves 0-3 (deferred PV), LDS store moved to end of iteration
# speedup vs baseline: 1.2066x; 1.0006x over previous
; #define LAS __attribute__((address_space(3)))
; #define OPQV(x) asm volatile("" : "+v"(x))
; DEV void kv_store(LAS unsigned char* lds, const KVRegs& r, int buf, int tid) {
;     const int key = tid >> 3, c8 = (tid & 7) * 8;
;     unsigned kw = AT_KS + buf * 9216 + (key * 72 + c8) * 2, vw = AT_VT + buf * 9216 + ((tid >> 6) * 8 * 72 + (tid & 63)) * 2; OPQV(kw); OPQV(vw);
;     *(LAS u32x4*)(lds + kw) = r.k;
; #pragma unroll
;     for (int j = 0; j < 4; ++j) { *(LAS bf16_t*)(lds + vw + j * 288) = (bf16_t)(r.v[j] & 0xffffu); *(LAS bf16_t*)(lds + vw + j * 288 + 144) = (bf16_t)(r.v[j] >> 16); }
; }
; DEV void attn_item(LAS unsigned char* lds, const bf16_t* P, const bf16_t* QB, const bf16_t* KV, const bf16_t* KC, const bf16_t* VC, const float* rel_bias, bf16_t* OB, int b, int g, int qt) {
;     ...
;     const unsigned mymask = MASK[qs * 16 + fr];
;     unsigned anym = MASK[lane];
; #pragma unroll
;     for (int o = 32; o >= 1; o >>= 1) anym |= __shfl_xor(anym, o);
;     anym = __builtin_amdgcn_readfirstlane(anym);
;     {
;         float cbias[2]; cbias[0] = *(const LAS float*)(lds + btb + 512); cbias[1] = *(const LAS float*)(lds + btb + 512 + 516);
;         float mrun[2] = {NEG_, NEG_}, lrun[2] = {0.f, 0.f}; f32x4 O[2][4];
; #pragma unroll
;         for (int hh = 0; hh < 2; ++hh)
; #pragma unroll
;             for (int dt = 0; dt < 4; ++dt) O[hh][dt] = (f32x4){0.f, 0.f, 0.f, 0.f};
;         unsigned rem = anym & (qt >= 31 ? 0xffffffffu : ((2u << qt) - 1u)); rem &= ~1u;
;         int mode = 1, j = 0, buf = 0;
;         for (;;) {
;             kv_store(lds, pre, buf, tid);
;             __syncthreads();
.LBB0_257:
	v_cmp_gt_i32_e32 vcc, s93, v7
	s_and_b64 s[4:5], s[4:5], vcc
	v_cndmask_b32_e64 v7, 0, 1, s[4:5]
	v_cmp_ne_u32_e32 vcc, 0, v7
	s_and_saveexec_b64 s[4:5], s[42:43]
	v_lshl_add_u32 v7, v66, 2, 0
	v_lshrrev_b64 v[60:61], v67, vcc
	v_add_u32_e32 v7, 0x11c00, v7
	v_or_b32_e32 v60, s92, v60
	ds_write_b32 v7, v60
	s_or_b64 exec, exec, s[4:5]
	s_add_i32 s4, 0, 0x11c00
	v_lshl_add_u32 v7, v152, 2, s4
	s_waitcnt lgkmcnt(0)
	s_barrier
	ds_read_b32 v7, v7
	v_lshlrev_b32_e32 v60, 2, v137
	v_lshlrev_b32_e32 v61, 2, v136
	v_add3_u32 v60, s4, v60, v61
	ds_read_b32 v127, v60
	s_waitcnt lgkmcnt(1)
	ds_bpermute_b32 v61, v144, v7
	v_and_b32_e32 v60, 0xffff0000, v149
	v_lshlrev_b32_e32 v126, 16, v149
	s_lshl_b32 s5, 2, s15
	s_waitcnt lgkmcnt(1)
	v_pk_fma_f32 v[134:135], v[126:127], v[2:3], 0 op_sel_hi:[0,1,0]
	s_waitcnt lgkmcnt(0)
	v_or_b32_e32 v7, v61, v7
	v_pk_fma_f32 v[116:117], v[60:61], v[44:45], 0 op_sel_hi:[0,1,0]
	ds_bpermute_b32 v44, v143, v7
	v_xor_b32_e32 v3, 4, v213
	v_pk_fma_f32 v[130:131], v[126:127], v[4:5], 0 op_sel_hi:[0,1,0]
	v_pk_fma_f32 v[132:133], v[126:127], v[32:33], 0 op_sel_hi:[0,1,0]
	s_add_i32 s5, s5, -1
	s_waitcnt lgkmcnt(0)
	v_or_b32_e32 v7, v44, v7
	v_xor_b32_e32 v44, 8, v213
	v_cmp_lt_i32_e32 vcc, v44, v153
	s_and_b32 s5, s5, -2
	s_cmp_lt_u32 s15, 31
	v_cndmask_b32_e32 v44, v213, v44, vcc
	v_lshlrev_b32_e32 v44, 2, v44
	ds_bpermute_b32 v44, v44, v7
	v_cmp_lt_i32_e32 vcc, v3, v153
	s_cselect_b32 s5, s5, -2
	v_pk_fma_f32 v[114:115], v[60:61], v[46:47], 0 op_sel_hi:[0,1,0]
	v_cndmask_b32_e32 v3, v213, v3, vcc
	s_waitcnt lgkmcnt(0)
	v_or_b32_e32 v2, v44, v7
	v_lshlrev_b32_e32 v3, 2, v3
	ds_bpermute_b32 v3, v3, v2
	v_pk_fma_f32 v[110:111], v[60:61], v[50:51], 0 op_sel_hi:[0,1,0]
	v_pk_fma_f32 v[112:113], v[60:61], v[48:49], 0 op_sel_hi:[0,1,0]
	v_pk_fma_f32 v[104:105], v[60:61], v[54:55], 0 op_sel_hi:[0,1,0]
	v_pk_fma_f32 v[108:109], v[60:61], v[52:53], 0 op_sel_hi:[0,1,0]
	s_waitcnt lgkmcnt(0)
	v_or_b32_e32 v4, v3, v2
	v_xor_b32_e32 v2, 2, v213
	v_cmp_lt_i32_e32 vcc, v2, v153
	v_and_b32_e32 v3, 0xffff0000, v148
	v_pk_fma_f32 v[102:103], v[60:61], v[58:59], 0 op_sel_hi:[0,1,0]
	v_cndmask_b32_e32 v2, v213, v2, vcc
	v_lshlrev_b32_e32 v2, 2, v2
	ds_bpermute_b32 v5, v2, v4
	v_lshlrev_b32_e32 v2, 16, v148
	v_mov_b32_e32 v148, 0
	v_pk_fma_f32 v[106:107], v[60:61], v[56:57], 0 op_sel_hi:[0,1,0]
	v_pk_fma_f32 v[128:129], v[126:127], v[34:35], 0 op_sel_hi:[0,1,0]
	s_waitcnt lgkmcnt(0)
	v_or_b32_e32 v32, v5, v4
	v_xor_b32_e32 v4, 1, v213
	v_cmp_lt_i32_e32 vcc, v4, v153
	v_pk_fma_f32 v[120:121], v[126:127], v[38:39], 0 op_sel_hi:[0,1,0]
	v_pk_fma_f32 v[124:125], v[126:127], v[36:37], 0 op_sel_hi:[0,1,0]
	v_cndmask_b32_e32 v4, v213, v4, vcc
	v_lshlrev_b32_e32 v4, 2, v4
	ds_bpermute_b32 v33, v4, v32
	v_pk_fma_f32 v[118:119], v[126:127], v[42:43], 0 op_sel_hi:[0,1,0]
	v_pk_fma_f32 v[122:123], v[126:127], v[40:41], 0 op_sel_hi:[0,1,0]
	v_and_b32_e32 v5, 0xffff0000, v147
	v_lshlrev_b32_e32 v4, 16, v147
	s_waitcnt lgkmcnt(0)
	v_or_b32_e32 v32, v33, v32
	v_add_u32_e32 v33, 0x200, v142
	ds_read2_b32 v[136:137], v33 offset1:129
	v_readfirstlane_b32 s4, v32
	v_mul_lo_u32 v32, v100, s24
	v_or_b32_e32 v32, v32, v152
	v_lshl_add_u32 v146, v32, 1, v221
	v_sub_u32_e64 v32, s15, 8 clamp
	v_mov_b32_e32 v7, v60
	s_mov_b32 s97, 1
	s_and_b32 s95, s4, s5
	v_readfirstlane_b32 s94, v32
	s_sub_i32 s17, 23, s17
	v_add_u32_e32 v145, 0, v145
	s_mov_b32 s50, 0
	v_mov_b32_e32 v150, 0xf149f2ca
	v_mov_b32_e32 v147, 0
	v_mov_b32_e32 v149, 0xf149f2ca
	v_mov_b32_e32 v151, 0
	v_mov_b32_e32 v48, 0
	v_mov_b32_e32 v49, v148
	v_mov_b32_e32 v50, v148
	v_mov_b32_e32 v51, v148
	v_mov_b32_e32 v36, 0
	v_mov_b32_e32 v37, v148
	v_mov_b32_e32 v38, v148
	v_mov_b32_e32 v39, v148
	v_mov_b32_e32 v40, 0
	v_mov_b32_e32 v41, v148
	v_mov_b32_e32 v42, v148
	v_mov_b32_e32 v43, v148
	v_mov_b32_e32 v32, 0
	v_mov_b32_e32 v33, v148
	v_mov_b32_e32 v34, v148
	v_mov_b32_e32 v35, v148
	v_mov_b32_e32 v60, 0
	v_mov_b32_e32 v61, v148
	v_mov_b32_e32 v62, v148
	v_mov_b32_e32 v63, v148
	v_mov_b32_e32 v52, 0
	v_mov_b32_e32 v53, v148
	v_mov_b32_e32 v54, v148
	v_mov_b32_e32 v55, v148
	v_mov_b32_e32 v56, 0
	v_mov_b32_e32 v57, v148
	v_mov_b32_e32 v58, v148
	v_mov_b32_e32 v59, v148
	v_mov_b32_e32 v44, 0
	v_mov_b32_e32 v45, v148
	v_mov_b32_e32 v46, v148
	v_mov_b32_e32 v47, v148
	v_readfirstlane_b32 s100, v210
	s_mov_b32 s98, 0
	s_waitcnt vmcnt(1)
	ds_write_b128 v139, v[24:27]
	s_waitcnt vmcnt(0)
	ds_write_b16 v146, v28
	ds_write_b16_d16_hi v146, v28 offset:144
	ds_write_b16 v146, v29 offset:288
	ds_write_b16_d16_hi v146, v29 offset:432
	ds_write_b16 v146, v30 offset:576
	ds_write_b16_d16_hi v146, v30 offset:720
	ds_write_b16 v146, v31 offset:864
	ds_write_b16_d16_hi v146, v31 offset:1008
	s_lshr_b32 s100, s100, 8
	s_mul_i32 s100, s100, 3
	s_waitcnt lgkmcnt(0)
	s_barrier
.LBB0_260:
	s_cmp_eq_u32 s97, 1
	s_cselect_b64 s[46:47], -1, 0
	s_cmp_lg_u32 s97, 1
	s_mov_b64 s[4:5], -1
	s_cbranch_scc0 .LBB0_262
	s_add_i32 s52, s50, 1
	s_cmp_lt_i32 s50, s15
	s_mov_b64 s[4:5], 0
	s_cselect_b64 s[54:55], -1, 0

; #define LAS __attribute__((address_space(3)))
; DEV void attn_tile(LAS unsigned char* lds, const bf16x8 (&qf)[2][2], int tl, int kpos0, int mode, bool near, bool rowsel, const float (&cbias)[2],
;                    unsigned kb, unsigned vb_, unsigned btb, int g4, float (&mrun)[2], float (&lrun)[2], f32x4 (&O)[2][4]) {
;     f32x4 sc[2][4];
;     float ci[2];
; #pragma unroll
;     for (int hh = 0; hh < 2; ++hh) { const float mne = mrun[hh] < -1e29f ? 0.f : mrun[hh];
;         ci[hh] = near ? -mne : (((mode == 1 && !rowsel) ? NEG_ : cbias[hh]) - mne); }
;     {
;         bf16x8 kf[4][2];
; #pragma unroll
;         for (int kt = 0; kt < 4; ++kt) { kf[kt][0] = *(const LAS bf16x8*)(lds + kb + kt * 2304); kf[kt][1] = *(const LAS bf16x8*)(lds + kb + kt * 2304 + 64); }
;         __builtin_amdgcn_sched_barrier(0);
; #pragma unroll
;         for (int kt = 0; kt < 4; ++kt)
; #pragma unroll
;             for (int hh = 0; hh < 2; ++hh) sc[hh][kt] = __builtin_amdgcn_mfma_f32_16x16x32_bf16(kf[kt][0], qf[hh][0], (f32x4){ci[hh], ci[hh], ci[hh], ci[hh]}, 0, 0, 0);
; #pragma unroll
;         for (int kt = 0; kt < 4; ++kt)
; #pragma unroll
;             for (int hh = 0; hh < 2; ++hh) sc[hh][kt] = __builtin_amdgcn_mfma_f32_16x16x32_bf16(kf[kt][1], qf[hh][1], sc[hh][kt], 0, 0, 0);
;     }
; DEV void attn_item(LAS unsigned char* lds, const bf16_t* P, const bf16_t* QB, const bf16_t* KV, const bf16_t* KC, const bf16_t* VC, const float* rel_bias, bf16_t* OB, int b, int g, int qt) {
;     ...
;             if (mode == 1) { if (rem != 0u) { j_n = __builtin_ctz(rem); rem &= rem - 1u; } else { mode_n = 2; j_n = max(0, qt - 8); } }
;             else { j_n = j + 1; more = j_n <= qt; }
;             if (more) { const bf16_t* base = pbg + (size_t)j_n * 64 * 64 + (mode_n == 1 ? 2 : 4) * KV_TENSOR; pre = kv_fetch(base, base + KV_TENSOR, tid); }
;             const bool near = (j >= qt - 2) || (mode == 2 && j == qt - 8);
;             attn_tile(lds, qf, tl, j * 64, mode, near, ((mymask >> j) & 1u) != 0u, cbias, kb + buf * 9216, vb1 + buf * 9216, btb, g4, mrun, lrun, O);
.LBB0_269:
	s_cmp_lg_u32 s96, s97
	s_cselect_b32 s99, 0x100, 0
	s_cmp_lg_u64 s[92:93], 0
	s_cselect_b32 s99, 0x100, s99
	s_or_b32 s99, s99, s97
	s_cmp_eq_u32 s100, 1
	s_cbranch_scc1 .Lst_y_entry
.Lst_xx:
	s_min_u32 s100, s100, 1
	s_mov_b32 s101, s99
	s_cmp_ge_i32 s50, s36
	s_cselect_b64 s[4:5], -1, 0
	s_cmp_eq_u32 s97, 2
	s_cselect_b64 s[6:7], -1, 0
	s_cmp_eq_u32 s50, s17
	s_cselect_b64 s[42:43], -1, 0
	s_and_b64 s[6:7], s[6:7], s[42:43]
	s_or_b64 s[4:5], s[4:5], s[6:7]
	v_lshrrev_b32_e32 v64, s50, v127
	v_and_b32_e32 v64, 1, v64
	s_cmp_lg_u32 s97, 1
	v_cmp_eq_u32_e64 s[48:49], 1, v64
	s_cselect_b64 s[6:7], -1, 0
	s_or_b64 vcc, s[6:7], s[48:49]
	v_cmp_gt_f32_e64 s[44:45], s65, v149
	v_cndmask_b32_e32 v65, v223, v136, vcc
	v_cmp_gt_f32_e64 s[42:43], s65, v150
	v_cndmask_b32_e64 v64, v149, 0, s[44:45]
	v_sub_f32_e32 v65, v65, v64
	v_cndmask_b32_e64 v64, v65, -v64, s[4:5]
	v_cndmask_b32_e64 v65, v150, 0, s[42:43]
	v_cndmask_b32_e32 v66, v223, v137, vcc
	v_sub_f32_e32 v66, v66, v65
	v_cndmask_b32_e64 v68, v66, -v65, s[4:5]
	v_add_u32_e32 v65, s98, v141
	ds_read_b128 v[72:75], v65
	ds_read_b128 v[76:79], v65 offset:64
	ds_read_b128 v[80:83], v65 offset:2304
	ds_read_b128 v[84:87], v65 offset:2368
	ds_read_b128 v[88:91], v65 offset:4608
	ds_read_b128 v[154:157], v65 offset:4672
	ds_read_b128 v[92:95], v65 offset:6912
	ds_read_b128 v[158:161], v65 offset:6976
	v_mov_b32_e32 v65, v64
	v_mov_b32_e32 v66, v64
	v_mov_b32_e32 v67, v64
	v_mov_b32_e32 v69, v68
	v_mov_b32_e32 v70, v68
	v_mov_b32_e32 v71, v68
	s_waitcnt lgkmcnt(7)
	v_mfma_f32_16x16x32_bf16 v[162:165], v[72:75], v[8:11], v[64:67]
	s_mov_b64 s[6:7], -1
	s_and_b64 vcc, exec, s[4:5]
	v_mfma_f32_16x16x32_bf16 v[72:75], v[72:75], v[16:19], v[68:71]
	v_add_u32_e32 v228, s98, v145
	v_add_u32_e32 v229, 0x800, v228
	v_add_u32_e32 v230, 0x1000, v228
	v_add_u32_e32 v231, 0x1800, v228
	ds_read2_b64 v[232:235], v228 offset1:4
	ds_read2_b64 v[236:239], v228 offset0:8 offset1:12
	ds_read2_b64 v[240:243], v229 offset0:32 offset1:36
	ds_read2_b64 v[244:247], v229 offset0:40 offset1:44
	ds_read2_b64 v[248:251], v230 offset0:64 offset1:68
	ds_read2_b64 v[198:201], v230 offset0:72 offset1:76
	ds_read2_b64 v[202:205], v231 offset0:96 offset1:100
	ds_read2_b64 v[206:209], v231 offset0:104 offset1:108
	s_waitcnt lgkmcnt(13)
	v_mfma_f32_16x16x32_bf16 v[166:169], v[80:83], v[8:11], v[64:67]
	v_mfma_f32_16x16x32_bf16 v[80:83], v[80:83], v[16:19], v[68:71]
	s_waitcnt lgkmcnt(11)
	v_mfma_f32_16x16x32_bf16 v[180:183], v[88:91], v[8:11], v[64:67]
	v_mfma_f32_16x16x32_bf16 v[184:187], v[88:91], v[16:19], v[68:71]
	s_waitcnt lgkmcnt(9)
	v_mfma_f32_16x16x32_bf16 v[188:191], v[92:95], v[8:11], v[64:67]
	v_mfma_f32_16x16x32_bf16 v[68:71], v[92:95], v[16:19], v[68:71]
	v_mfma_f32_16x16x32_bf16 v[92:95], v[76:79], v[12:15], v[162:165]
	v_mfma_f32_16x16x32_bf16 v[76:79], v[76:79], v[20:23], v[72:75]
	v_mfma_f32_16x16x32_bf16 v[88:91], v[84:87], v[12:15], v[166:169]
	v_mfma_f32_16x16x32_bf16 v[72:75], v[84:87], v[20:23], v[80:83]
	v_mfma_f32_16x16x32_bf16 v[84:87], v[154:157], v[12:15], v[180:183]
	v_mfma_f32_16x16x32_bf16 v[64:67], v[154:157], v[20:23], v[184:187]
	s_waitcnt lgkmcnt(8)
	v_mfma_f32_16x16x32_bf16 v[80:83], v[158:161], v[12:15], v[188:191]
	v_mfma_f32_16x16x32_bf16 v[68:71], v[158:161], v[20:23], v[68:71]
	s_cbranch_vccnz .LBB0_271
	s_mov_b64 s[6:7], 0

; DEV void attn_tile(LAS unsigned char* lds, const bf16x8 (&qf)[2][2], int tl, int kpos0, int mode, bool near, bool rowsel, const float (&cbias)[2],
;                    unsigned kb, unsigned vb_, unsigned btb, int g4, float (&mrun)[2], float (&lrun)[2], f32x4 (&O)[2][4]) {
;     ...
;         float rs = 0.f;
; #pragma unroll
;         for (int kt = 0; kt < 4; ++kt)
; #pragma unroll
;             for (int r = 0; r < 4; ++r) { const float p = __builtin_amdgcn_exp2f(sc[hh][kt][r]); sc[hh][kt][r] = p; rs += p; }
;         lrun[hh] += rs;
; #pragma unroll
;         for (int kc = 0; kc < 2; ++kc) { u32x4 w; w.x = cvt_pk_bf16(sc[hh][2 * kc][0], sc[hh][2 * kc][1]); w.y = cvt_pk_bf16(sc[hh][2 * kc][2], sc[hh][2 * kc][3]);
;             w.z = cvt_pk_bf16(sc[hh][2 * kc + 1][0], sc[hh][2 * kc + 1][1]); w.w = cvt_pk_bf16(sc[hh][2 * kc + 1][2], sc[hh][2 * kc + 1][3]); pf[hh][kc] = as_bf16x8(w); }
;     }
; #pragma unroll
;     for (int dt = 0; dt < 4; ++dt)
; #pragma unroll
;         for (int kc = 0; kc < 2; ++kc) {
;             const u32x2 va = *(const LAS u32x2*)(lds + vb_ + dt * 2304 + kc * 64);
;             const u32x2 vb = *(const LAS u32x2*)(lds + vb_ + dt * 2304 + kc * 64 + 32);
;             const bf16x8 vf = as_bf16x8((u32x4){va.x, va.y, vb.x, vb.y});
; #pragma unroll
;             for (int hh = 0; hh < 2; ++hh) O[hh][dt] = __builtin_amdgcn_mfma_f32_16x16x32_bf16(vf, pf[hh][kc], O[hh][dt], 0, 0, 0);
;         }
; }
; DEV void attn_item(LAS unsigned char* lds, const bf16_t* P, const bf16_t* QB, const bf16_t* KV, const bf16_t* KC, const bf16_t* VC, const float* rel_bias, bf16_t* OB, int b, int g, int qt) {
;     ...
;             kv_store(lds, pre, buf, tid);
;             __syncthreads();
;             int mode_n = mode, j_n = 0; bool more = true;
;             if (mode == 1) { if (rem != 0u) { j_n = __builtin_ctz(rem); rem &= rem - 1u; } else { mode_n = 2; j_n = max(0, qt - 8); } }
;             else { j_n = j + 1; more = j_n <= qt; }
;             if (more) { const bf16_t* base = pbg + (size_t)j_n * 64 * 64 + (mode_n == 1 ? 2 : 4) * KV_TENSOR; pre = kv_fetch(base, base + KV_TENSOR, tid); }
;             const bool near = (j >= qt - 2) || (mode == 2 && j == qt - 8);
;             attn_tile(lds, qf, tl, j * 64, mode, near, ((mymask >> j) & 1u) != 0u, cbias, kb + buf * 9216, vb1 + buf * 9216, btb, g4, mrun, lrun, O);
;             if (mode_n != mode || !more) {
; #pragma unroll
.LBB0_277:
	s_cmp_eq_u32 s100, 0
	s_cbranch_scc1 .Lst_y_entry
.Lst_zz:
	s_andn2_b64 vcc, exec, s[92:93]
	s_cbranch_vccz .Lst_exit
	s_xor_b32 s98, s98, 0x2400
	v_add_u32_e32 v228, s98, v139
	v_add_u32_e32 v229, s98, v146
	s_waitcnt vmcnt(1)
	ds_write_b128 v228, v[24:27]
	s_waitcnt vmcnt(0)
	ds_write_b16 v229, v28
	ds_write_b16_d16_hi v229, v28 offset:144
	ds_write_b16 v229, v29 offset:288
	ds_write_b16_d16_hi v229, v29 offset:432
	ds_write_b16 v229, v30 offset:576
	ds_write_b16_d16_hi v229, v30 offset:720
	ds_write_b16 v229, v31 offset:864
	ds_write_b16_d16_hi v229, v31 offset:1008
	s_waitcnt lgkmcnt(0)
	s_barrier
	s_mov_b32 s97, s96
	s_mov_b32 s50, s52
	s_branch .LBB0_260
.Lst_exit:
	s_cmp_eq_u32 s100, 0
	s_cbranch_scc1 .LBB0_157
	s_mov_b32 s100, 2
.Lst_y_entry:
	v_add_f32_e32 v92, 0, v92
	v_add_f32_e32 v92, v93, v92
	v_add_f32_e32 v92, v94, v92
	v_add_f32_e32 v92, v95, v92
	v_add_f32_e32 v88, v88, v92
	v_add_f32_e32 v88, v89, v88
	v_add_f32_e32 v88, v90, v88
	v_add_f32_e32 v88, v91, v88
	v_add_f32_e32 v88, v153, v88
	v_add_f32_e32 v88, v154, v88
	v_add_f32_e32 v88, v155, v88
	v_add_f32_e32 v88, v156, v88
	v_add_f32_e32 v88, v157, v88
	v_exp_f32_e32 v76, v76
	v_add_f32_e32 v88, v158, v88
	v_exp_f32_e32 v77, v77
	v_add_f32_e32 v88, v159, v88
	v_exp_f32_e32 v78, v78
	v_add_f32_e32 v88, v160, v88
	v_exp_f32_e32 v79, v79
	v_add_f32_e32 v151, v151, v88
	v_add_f32_e32 v88, 0, v76
	v_exp_f32_e32 v72, v72
	v_add_f32_e32 v88, v77, v88
	v_exp_f32_e32 v73, v73
	v_add_f32_e32 v88, v78, v88
	v_exp_f32_e32 v74, v74
	v_add_f32_e32 v88, v79, v88
	v_exp_f32_e32 v75, v75
	v_add_f32_e32 v88, v72, v88
	v_exp_f32_e32 v64, v64
	v_add_f32_e32 v88, v73, v88
	v_exp_f32_e32 v65, v65
	v_add_f32_e32 v88, v74, v88
	v_exp_f32_e32 v66, v66
	v_add_f32_e32 v88, v75, v88
	v_exp_f32_e32 v67, v67
	v_add_f32_e32 v88, v64, v88
	v_exp_f32_e32 v89, v68
	v_add_f32_e32 v88, v65, v88
	v_add_f32_e32 v88, v66, v88
	v_add_f32_e32 v88, v67, v88
	v_add_f32_e32 v68, v89, v88
	v_exp_f32_e32 v88, v69
	v_exp_f32_e32 v90, v70
	v_exp_f32_e32 v91, v71
	v_add_f32_e32 v68, v88, v68
	v_add_f32_e32 v68, v90, v68
	v_add_f32_e32 v68, v91, v68
	v_add_f32_e32 v148, v148, v68
	v_cvt_pk_bf16_f32 v68, v76, v77
	v_cvt_pk_bf16_f32 v69, v78, v79
	v_cvt_pk_bf16_f32 v70, v72, v73
	v_cvt_pk_bf16_f32 v71, v74, v75
	v_cvt_pk_bf16_f32 v64, v64, v65
	v_cvt_pk_bf16_f32 v65, v66, v67
	v_cvt_pk_bf16_f32 v66, v89, v88
	v_cvt_pk_bf16_f32 v67, v90, v91
	s_waitcnt lgkmcnt(7)
	v_mfma_f32_16x16x32_bf16 v[44:47], v[232:235], v[84:87], v[44:47]
	v_mfma_f32_16x16x32_bf16 v[32:35], v[232:235], v[68:71], v[32:35]
	s_waitcnt lgkmcnt(6)
	v_mfma_f32_16x16x32_bf16 v[44:47], v[236:239], v[80:83], v[44:47]
	v_mfma_f32_16x16x32_bf16 v[32:35], v[236:239], v[64:67], v[32:35]
	s_waitcnt lgkmcnt(5)
	v_mfma_f32_16x16x32_bf16 v[56:59], v[240:243], v[84:87], v[56:59]
	v_mfma_f32_16x16x32_bf16 v[40:43], v[240:243], v[68:71], v[40:43]
	s_waitcnt lgkmcnt(4)
	v_mfma_f32_16x16x32_bf16 v[56:59], v[244:247], v[80:83], v[56:59]
	v_mfma_f32_16x16x32_bf16 v[40:43], v[244:247], v[64:67], v[40:43]
	s_waitcnt lgkmcnt(3)
	v_mfma_f32_16x16x32_bf16 v[52:55], v[248:251], v[84:87], v[52:55]
	v_mfma_f32_16x16x32_bf16 v[36:39], v[248:251], v[68:71], v[36:39]
	s_waitcnt lgkmcnt(2)
	v_mfma_f32_16x16x32_bf16 v[52:55], v[198:201], v[80:83], v[52:55]
	v_mfma_f32_16x16x32_bf16 v[36:39], v[198:201], v[64:67], v[36:39]
	s_waitcnt lgkmcnt(1)
	v_mfma_f32_16x16x32_bf16 v[48:51], v[202:205], v[68:71], v[48:51]
	v_mfma_f32_16x16x32_bf16 v[60:63], v[202:205], v[84:87], v[60:63]
	s_waitcnt lgkmcnt(0)
	v_mfma_f32_16x16x32_bf16 v[60:63], v[206:209], v[80:83], v[60:63]
	v_mfma_f32_16x16x32_bf16 v[48:51], v[206:209], v[64:67], v[48:51]
	s_bitcmp1_b32 s101, 8
	s_cbranch_scc0 .LBB0_283
	ds_bpermute_b32 v64, v143, v151
	s_and_b32 s6, s101, 0xff
	s_lshl_b32 s6, s6, 1
	v_mov_b32_e32 v66, 0
	s_waitcnt lgkmcnt(0)
	v_add_f32_e32 v64, v151, v64
	ds_bpermute_b32 v65, v144, v64
	s_waitcnt lgkmcnt(0)
	v_add_f32_e32 v65, v64, v65
	v_mov_b32_e32 v64, 0
	v_cmp_lt_f32_e32 vcc, 0, v65
	s_and_saveexec_b64 s[4:5], vcc
	s_cbranch_execz .LBB0_280
	s_cmp_eq_u32 s6, 1
	s_cselect_b64 vcc, -1, 0
	s_cmp_eq_u32 s6, 2
	v_cndmask_b32_e32 v66, v126, v7, vcc
	s_cselect_b64 vcc, -1, 0
	s_cmp_eq_u32 s6, 3
	v_cndmask_b32_e32 v66, v66, v2, vcc
	s_cselect_b64 vcc, -1, 0
	s_cmp_eq_u32 s6, 4
	v_cndmask_b32_e32 v66, v66, v3, vcc
	s_cselect_b64 vcc, -1, 0
	s_cmp_eq_u32 s6, 5
	v_cndmask_b32_e32 v66, v66, v4, vcc
	s_cselect_b64 vcc, -1, 0
	v_cndmask_b32_e32 v66, v66, v5, vcc
	v_div_scale_f32 v67, s[42:43], v65, v65, v66
	v_rcp_f32_e32 v68, v67
	s_nop 0
	v_fma_f32 v69, -v67, v68, 1.0
	v_fmac_f32_e32 v68, v69, v68
	v_div_scale_f32 v69, vcc, v66, v65, v66
	v_mul_f32_e32 v70, v69, v68
	v_fma_f32 v71, -v67, v70, v69
	v_fmac_f32_e32 v70, v71, v68
	v_fma_f32 v67, -v67, v70, v69
	v_div_fmas_f32 v67, v67, v68, v70
	v_div_fixup_f32 v66, v67, v65, v66

; DEV void attn_item(LAS unsigned char* lds, const bf16_t* P, const bf16_t* QB, const bf16_t* KV, const bf16_t* KC, const bf16_t* VC, const float* rel_bias, bf16_t* OB, int b, int g, int qt) {
;     ...
;             if (mode_n != mode || !more) {
; #pragma unroll
;                 for (int hh = 0; hh < 2; ++hh) { float lt = lrun[hh]; lt += __shfl_xor(lt, 16); lt += __shfl_xor(lt, 32); const float sc = lt > 0.f ? gate[mode][hh] / lt : 0.f;
; #pragma unroll
;                     for (int dt = 0; dt < 4; ++dt) { F[hh][dt] = F[hh][dt] + O[hh][dt] * sc; O[hh][dt] = (f32x4){0.f, 0.f, 0.f, 0.f}; }
;                     mrun[hh] = NEG_; lrun[hh] = 0.f; }
;             }
;             if (!more) break;
;             mode = mode_n; j = j_n; buf ^= 1;
;         }
.LBB0_283:
	s_cmp_eq_u32 s100, 0
	s_cbranch_scc1 .Lst_zz
	s_cmp_eq_u32 s100, 1
	s_cbranch_scc1 .Lst_xx
	s_branch .LBB0_157

; __global__ void __launch_bounds__(512, 2) fwd_mega(Params p_unused) {
;     extern __shared__ __attribute__((aligned(16))) unsigned char lds_raw[];
	.amdhsa_kernel _Z8fwd_mega6Params
		.amdhsa_group_segment_fixed_size 0
		.amdhsa_private_segment_fixed_size 0
		.amdhsa_kernarg_size 448
		.amdhsa_user_sgpr_count 2
		.amdhsa_user_sgpr_dispatch_ptr 0
		.amdhsa_user_sgpr_queue_ptr 0
		.amdhsa_user_sgpr_kernarg_segment_ptr 1
		.amdhsa_user_sgpr_dispatch_id 0
		.amdhsa_user_sgpr_kernarg_preload_length 0
		.amdhsa_user_sgpr_kernarg_preload_offset 0
		.amdhsa_user_sgpr_private_segment_size 0
		.amdhsa_uses_dynamic_stack 0
		.amdhsa_enable_private_segment 0
		.amdhsa_system_sgpr_workgroup_id_x 1
		.amdhsa_system_sgpr_workgroup_id_y 0
		.amdhsa_system_sgpr_workgroup_id_z 0
		.amdhsa_system_sgpr_workgroup_info 0
		.amdhsa_system_vgpr_workitem_id 2
		.amdhsa_next_free_vgpr 256
		.amdhsa_next_free_sgpr 102
		.amdhsa_accum_offset 256
		.amdhsa_reserve_vcc 1
		.amdhsa_float_round_mode_32 0
		.amdhsa_float_round_mode_16_64 0
		.amdhsa_float_denorm_mode_32 3
		.amdhsa_float_denorm_mode_16_64 3
		.amdhsa_dx10_clamp 1
		.amdhsa_ieee_mode 1
		.amdhsa_fp16_overflow 0
		.amdhsa_tg_split 0
		.amdhsa_exception_fp_ieee_invalid_op 0
		.amdhsa_exception_fp_denorm_src 0
		.amdhsa_exception_fp_ieee_div_zero 0
		.amdhsa_exception_fp_ieee_overflow 0
		.amdhsa_exception_fp_ieee_underflow 0
		.amdhsa_exception_fp_ieee_inexact 0
		.amdhsa_exception_int_div_zero 0
	.end_amdhsa_kernel

; __global__ void __launch_bounds__(512, 2) fwd_mega(Params p_unused) {
;     extern __shared__ __attribute__((aligned(16))) unsigned char lds_raw[];
amdhsa.kernels:
  - .agpr_count:     0
    .args:
      - .offset:         0
        .size:           192
        .value_kind:     by_value
      - .offset:         192
        .size:           4
        .value_kind:     hidden_block_count_x
      - .offset:         196
        .size:           4
        .value_kind:     hidden_block_count_y
      - .offset:         200
        .size:           4
        .value_kind:     hidden_block_count_z
      - .offset:         204
        .size:           2
        .value_kind:     hidden_group_size_x
      - .offset:         206
        .size:           2
        .value_kind:     hidden_group_size_y
      - .offset:         208
        .size:           2
        .value_kind:     hidden_group_size_z
      - .offset:         210
        .size:           2
        .value_kind:     hidden_remainder_x
      - .offset:         212
        .size:           2
        .value_kind:     hidden_remainder_y
      - .offset:         214
        .size:           2
        .value_kind:     hidden_remainder_z
      - .offset:         232
        .size:           8
        .value_kind:     hidden_global_offset_x
      - .offset:         240
        .size:           8
        .value_kind:     hidden_global_offset_y
      - .offset:         248
        .size:           8
        .value_kind:     hidden_global_offset_z
      - .offset:         256
        .size:           2
        .value_kind:     hidden_grid_dims
      - .offset:         280
        .size:           8
        .value_kind:     hidden_multigrid_sync_arg
      - .offset:         312
        .size:           4
        .value_kind:     hidden_dynamic_lds_size
    .group_segment_fixed_size: 0
    .kernarg_segment_align: 8
    .kernarg_segment_size: 448
    .language:       OpenCL C
    .language_version:
      - 2
      - 0
    .max_flat_workgroup_size: 512
    .name:           _Z8fwd_mega6Params
    .private_segment_fixed_size: 0
    .sgpr_count:     108
    .sgpr_spill_count: 158
    .symbol:         _Z8fwd_mega6Params.kd
    .uniform_work_group_size: 1
    .uses_dynamic_stack: false
    .vgpr_count:     256
    .vgpr_spill_count: 0
    .wavefront_size: 64
